# speedup vs baseline: 1.0384x; 1.0051x over previous
; template <int EPI> ...
;     ...
;   auto tile_desc = [&](int i, int& pm, int& pn, int& koff, bool& atom) {
;     koff = 0;
;     atom = false;
;     if (i < nA) {
;       tile_coords(startA + jA + i * perA, nM, nN, pm, pn);
;     } else {
;       int u = startB + jB + (i - nA) * perB;
;       pm = mini_pm;
;       pn = u % nN;
;       koff = (u / nN) * Kc;
;       atom = true;
;     }
;   };
.LBB0_182:
	s_cmp_ge_i32 s99, s95
	s_cselect_b64 s[82:83], -1, 0
	s_cmp_lt_i32 s99, s95
	s_mov_b64 s[40:41], -1
	s_cselect_b64 s[84:85], -1, 0
	s_and_b64 vcc, exec, s[82:83]
	s_cbranch_vccnz .LBB0_184
	s_mul_i32 s2, s99, s94
	s_add_i32 s2, s2, s58
	s_ashr_i32 s6, s2, 31
	s_lshr_b32 s6, s6, 27
	s_add_i32 s6, s2, s6
	s_ashr_i32 s7, s6, 5
	s_lshl_b32 s7, s7, 2
	s_sub_i32 s8, s77, s7
	s_min_i32 s8, s8, 4
	s_abs_i32 s9, s8
	v_cvt_f32_u32_e32 v0, s9
	s_sub_i32 s11, 0, s9
	s_andn2_b32 s6, s6, 31
	s_sub_i32 s6, s2, s6
	v_rcp_iflag_f32_e32 v0, v0
	s_abs_i32 s2, s6
	s_xor_b32 s10, s6, s8
	s_ashr_i32 s10, s10, 31
	v_mul_f32_e32 v0, 0x4f7ffffe, v0
	v_cvt_u32_f32_e32 v0, v0
	s_mov_b64 s[40:41], 0
	v_readfirstlane_b32 s20, v0
	s_mul_i32 s11, s11, s20
	s_mul_hi_u32 s11, s20, s11
	s_add_i32 s20, s20, s11
	s_mul_hi_u32 s11, s2, s20
	s_mul_i32 s20, s11, s9
	s_sub_i32 s2, s2, s20
	s_add_i32 s21, s11, 1
	s_sub_i32 s20, s2, s9
	s_cmp_ge_u32 s2, s9
	s_cselect_b32 s11, s21, s11
	s_cselect_b32 s2, s20, s2
	s_add_i32 s20, s11, 1
	s_cmp_ge_u32 s2, s9
	s_cselect_b32 s2, s20, s11
	s_xor_b32 s2, s2, s10
	s_sub_i32 s2, s2, s10
	s_mul_i32 s8, s2, s8
	s_sub_i32 s6, s6, s8
	s_add_i32 s7, s6, s7
	s_sub_i32 s7, s77, s7
	s_add_i32 s7, s7, -1

; template <int EPI> ...
;     ...
;   auto tile_desc = [&](int i, int& pm, int& pn, int& koff, bool& atom) {
;     koff = 0;
;     atom = false;
;     if (i < nA) {
;       tile_coords(startA + jA + i * perA, nM, nN, pm, pn);
;     } else {
;       int u = startB + jB + (i - nA) * perB;
;       pm = mini_pm;
;       pn = u % nN;
;       koff = (u / nN) * Kc;
;       atom = true;
;     }
;   };
.LBB0_191:
	s_andn2_b64 vcc, exec, s[50:51]
	s_mov_b32 s8, s56
	s_cbranch_vccnz .LBB0_193
	s_mul_i32 s7, s99, s94
	s_add_i32 s7, s7, s58
	s_ashr_i32 s8, s7, 31
	s_lshr_b32 s8, s8, 27
	s_add_i32 s8, s7, s8
	s_ashr_i32 s9, s8, 5
	s_lshl_b32 s9, s9, 2
	s_sub_i32 s10, s77, s9
	s_min_i32 s10, s10, 4
	s_abs_i32 s11, s10
	v_cvt_f32_u32_e32 v0, s11
	s_sub_i32 s21, 0, s11
	s_andn2_b32 s8, s8, 31
	s_sub_i32 s8, s7, s8
	v_rcp_iflag_f32_e32 v0, v0
	s_abs_i32 s7, s8
	s_xor_b32 s20, s8, s10
	s_ashr_i32 s20, s20, 31
	v_mul_f32_e32 v0, 0x4f7ffffe, v0
	v_cvt_u32_f32_e32 v0, v0
	s_mov_b64 s[40:41], 0
	v_readfirstlane_b32 s28, v0
	s_mul_i32 s21, s21, s28
	s_mul_hi_u32 s21, s28, s21
	s_add_i32 s28, s28, s21
	s_mul_hi_u32 s21, s7, s28
	s_mul_i32 s28, s21, s11
	s_sub_i32 s7, s7, s28
	s_add_i32 s29, s21, 1
	s_sub_i32 s28, s7, s11
	s_cmp_ge_u32 s7, s11
	s_cselect_b32 s21, s29, s21
	s_cselect_b32 s7, s28, s7
	s_add_i32 s28, s21, 1
	s_cmp_ge_u32 s7, s11
	s_cselect_b32 s7, s28, s21
	s_xor_b32 s7, s7, s20
	s_sub_i32 s7, s7, s20
	s_mul_i32 s10, s7, s10
	s_sub_i32 s8, s8, s10
	s_add_i32 s8, s8, s9
	s_sub_i32 s8, s77, s8
	s_add_i32 s8, s8, -1

; template <int EPI> ...
;     ...
;   for (int i = 0; i < nA + nB; ++i) {
;     int pm, pn, koff;
;     bool atom;
;     tile_desc(i, pm, pn, koff, atom);
;     const int kk = atom ? Kc : K;
;     int brow = pm * 256, bcol = pn * 256;
;     void* o = outp;
;     int orow = brow;
;     if (EPI == 0) {
;       if (brow < USPLIT) {
;         o = (void*)p.out;
;       } else {
;         o = (void*)(p.ws + OFF_X);
;         orow = brow - USPLIT;
;       }
;     }
;     if (EPI == 1 && atom) {
;       o = (void*)((float*)(p.ws + OFF_PART) + (long)(koff / Kc) * (256 * DM));
;       orow = 0;
;     }
;     const char* nAb = nullptr;
;     const char* nBb = nullptr;
;     if (i + 1 < nA + nB) {
;       int pm2, pn2, koff2;
;       bool atom2;
;       tile_desc(i + 1, pm2, pn2, koff2, atom2);
;       nAb = (const char*)(A + koff2 + (long)pm2 * 256 * K);
;       nBb = (const char*)(Bt + koff2 + (long)pn2 * 256 * K);
;     }
;     gemm_tile<EPI>(A + koff, Bt + koff, kk, brow, bcol, o, orow, ldo, shm, ss_in, gain_out, atom ? nullptr : nout,
;                    ss_out, K, atom, pre, nAb, nBb);
.LBB0_404:
	s_mul_i32 s0, s76, s34
	s_add_i32 s0, s0, s77
	s_add_i32 s76, s76, 1
	s_cmp_ge_i32 s76, s49
	s_mov_b64 s[28:29], 0
	s_mov_b64 s[16:17], 0
	s_cbranch_scc1 .LBB0_406
	s_add_i32 s1, s0, s34
	s_mul_hi_i32 s2, s1, 0x2aaaaaab
	s_lshr_b32 s6, s2, 31
	s_ashr_i32 s2, s2, 4
	s_add_i32 s2, s2, s6
	s_lshl_b32 s7, s2, 2
	s_sub_i32 s6, 0xc1, s7
	s_min_i32 s8, s6, 4
	s_abs_i32 s6, s8
	v_cvt_f32_u32_e32 v0, s6
	s_sub_i32 s10, 0, s6
	s_mulk_i32 s2, 0x60
	s_sub_i32 s1, s1, s2
	v_rcp_iflag_f32_e32 v0, v0
	s_abs_i32 s2, s1
	s_xor_b32 s9, s1, s8
	s_ashr_i32 s9, s9, 31
	v_mul_f32_e32 v0, 0x4f7ffffe, v0
	v_cvt_u32_f32_e32 v0, v0
	s_nop 0
	v_readfirstlane_b32 s11, v0
	s_mul_i32 s10, s10, s11
	s_mul_hi_u32 s10, s11, s10
	s_add_i32 s11, s11, s10
	s_mul_hi_u32 s10, s2, s11
	s_mul_i32 s11, s10, s6
	s_sub_i32 s2, s2, s11
	s_add_i32 s14, s10, 1
	s_sub_i32 s11, s2, s6
	s_cmp_ge_u32 s2, s6
	s_cselect_b32 s10, s14, s10
	s_cselect_b32 s2, s11, s2
	s_add_i32 s11, s10, 1
	s_cmp_ge_u32 s2, s6
	s_cselect_b32 s2, s11, s10
	s_xor_b32 s2, s2, s9
	s_sub_i32 s6, s2, s9
	s_mul_i32 s2, s6, s8
	s_sub_i32 s1, s1, s2
	s_add_i32 s8, s1, s7
	s_sub_i32 s8, 0xc0, s8
	s_ashr_i32 s9, s8, 31
	s_lshl_b64 s[8:9], s[8:9], 20
	s_add_u32 s28, s68, s8
	s_addc_u32 s29, s69, s9
	s_ashr_i32 s7, s6, 31
	s_lshl_b64 s[6:7], s[6:7], 20
	s_add_u32 s16, s56, s6
	s_addc_u32 s17, s57, s7
.LBB0_406:
	s_mul_hi_i32 s1, s0, 0x2aaaaaab
	s_lshr_b32 s2, s1, 31
	s_ashr_i32 s1, s1, 4
	s_add_i32 s1, s1, s2
	s_lshl_b32 s2, s1, 2
	s_sub_i32 s6, 0xc1, s2
	s_min_i32 s6, s6, 4
	s_abs_i32 s7, s6
	v_cvt_f32_u32_e32 v0, s7
	s_xor_b64 s[8:9], s[12:13], -1
	s_sub_i32 s11, 0, s7
	s_mulk_i32 s1, 0x60
	v_rcp_iflag_f32_e32 v0, v0
	s_sub_i32 s0, s0, s1
	s_abs_i32 s1, s0
	s_xor_b32 s10, s0, s6
	v_mul_f32_e32 v0, 0x4f7ffffe, v0
	v_cvt_u32_f32_e32 v0, v0
	s_ashr_i32 s10, s10, 31
	v_mov_b32_e32 v133, v193
	v_readfirstlane_b32 s12, v0
	s_mul_i32 s11, s11, s12
	s_mul_hi_u32 s11, s12, s11
	s_add_i32 s12, s12, s11
	s_mul_hi_u32 s11, s1, s12
	s_mul_i32 s12, s11, s7
	s_sub_i32 s1, s1, s12
	s_add_i32 s13, s11, 1
	s_sub_i32 s12, s1, s7
	s_cmp_ge_u32 s1, s7
	s_cselect_b32 s11, s13, s11
	s_cselect_b32 s1, s12, s1
	s_add_i32 s12, s11, 1
	s_cmp_ge_u32 s1, s7
	s_cselect_b32 s1, s12, s11
	s_xor_b32 s1, s1, s10
	s_sub_i32 s1, s1, s10
	s_mul_i32 s6, s1, s6
	s_sub_i32 s0, s0, s6
	s_add_i32 s0, s2, s0
	s_sub_i32 s0, 0xc0, s0
	s_lshl_b32 s40, s0, 8
	s_lshl_b32 s14, s1, 8
	v_readfirstlane_b32 s2, v133
	s_lshl_b32 s2, s2, 4
	s_ashr_i32 s41, s40, 31
	s_ashr_i32 s15, s14, 31
	s_and_b32 s6, s2, 0x1c00
	s_lshl_b64 s[10:11], s[40:41], 12
	s_lshl_b64 s[12:13], s[14:15], 12
	s_cmp_lg_u32 0, -1
	s_cselect_b32 s2, 0, 0
	v_lshlrev_b32_e32 v0, 4, v133
	v_and_b32_e32 v2, 32, v133
	s_add_i32 s2, s6, s2
	v_lshrrev_b32_e32 v3, 3, v133
	v_bfe_u32 v4, v133, 2, 4
	v_bitop3_b32 v0, v0, v2, 48 bitop3:0x6c
	s_add_u32 s18, s68, s10
	v_and_or_b32 v0, v133, 64, v0
	v_and_or_b32 v2, v3, 48, v4
	s_addc_u32 s19, s69, s11
	v_ashrrev_i32_e32 v130, 8, v133
	v_lshl_or_b32 v132, v2, 12, v0
	s_add_u32 s72, s56, s12
	v_or_b32_e32 v131, 0x40000, v132
	s_addc_u32 s73, s57, s13
	s_mov_b64 s[74:75], -1
	s_andn2_b64 vcc, exec, s[8:9]
	v_cmp_eq_u32_e64 s[12:13], 1, v130
	s_cbranch_vccnz .LBB0_410
	s_cmp_lg_u32 0, -1
	s_cselect_b32 s7, 0, 0
	s_add_i32 s7, s7, s6
	s_add_i32 s15, s7, 0x10000
	s_mov_b32 m0, s15
	s_nop 0
	global_load_lds_dwordx4 v132, s[72:73]
	s_add_i32 s33, s7, 0x12000
	s_mov_b32 m0, s33
	s_nop 0
	global_load_lds_dwordx4 v131, s[72:73]
	s_add_i32 s41, s7, 0x2000
	s_mov_b32 m0, s2
	s_nop 0
	global_load_lds_dwordx4 v132, s[18:19]
	s_add_u32 s8, s72, 0x80000
	s_mov_b32 m0, s41
	s_nop 0
	global_load_lds_dwordx4 v131, s[18:19]
	s_addc_u32 s9, s73, 0
	s_add_i32 s38, s7, 0x14000
	s_mov_b32 m0, s38
	s_nop 0
	global_load_lds_dwordx4 v132, s[8:9]
	s_add_i32 s39, s7, 0x16000
	s_mov_b32 m0, s39
	s_nop 0
	global_load_lds_dwordx4 v131, s[8:9]
	s_add_u32 s8, s18, 0x80000
	s_addc_u32 s9, s19, 0
	s_add_i32 s47, s7, 0x4000
	s_mov_b32 m0, s47
	s_nop 0
	global_load_lds_dwordx4 v132, s[8:9]
	s_add_i32 s48, s7, 0x6000
	s_mov_b32 m0, s48
	s_nop 0
	global_load_lds_dwordx4 v131, s[8:9]
	s_and_saveexec_b64 s[50:51], s[12:13]
	s_cbranch_execz .LBB0_409
	s_barrier
